# GEMM1/GEMM3: leading wave half runs its tile epilogue before the align barrier (overlaps the trailing half's last MFMA segment)
# speedup vs baseline: 1.0047x; 1.0047x over previous
; DI unsigned cvt_pk_bf16(float lo, float hi) { f32x2 v = {lo, hi}; bf16v2 b = __builtin_convertvector(v, bf16v2); return __builtin_bit_cast(unsigned, b); }
; #define PG8_BAR __builtin_amdgcn_s_barrier()
;     DI void operator()(const f32x4 (&acc)[2][2][4][2], const Unit& u, int wr, int wc, int fr, int fq) const {
;         const int row0 = u.pm * BM + wr * 64 + fr; const int col0 = u.pn * BM + wc * 32 + 8 * fq;
;         float rs[2][4];
; #pragma unroll
;         for (int ai = 0; ai < 2; ++ai)
; #pragma unroll
;             for (int m = 0; m < 4; ++m) rs[ai][m] = ssq ? __builtin_amdgcn_rsqf(ssq[row0 + ai * HALF + m * 16] * (1.0f / 4096.0f) + 1e-6f) : 1.0f;
; #pragma unroll
;         for (int ai = 0; ai < 2; ++ai)
; #pragma unroll
;             for (int m = 0; m < 4; ++m) { bf16_t* rowp = O + (size_t)(row0 + ai * HALF + m * 16) * ldc + col0; const float s = rs[ai][m];
; #pragma unroll
;                 for (int bj = 0; bj < 2; ++bj) { const f32x4 v0 = acc[ai][bj][m][0] * s, v1 = acc[ai][bj][m][1] * s;
;                     u32x4 w; w.x = cvt_pk_bf16(v0[0], v0[1]); w.y = cvt_pk_bf16(v0[2], v0[3]); w.z = cvt_pk_bf16(v1[0], v1[1]); w.w = cvt_pk_bf16(v1[2], v1[3]);
;                     *(u32x4*)(rowp + bj * HALF) = w; } }
; template <class Epi, class Sched, bool ALIGN_EPI = false, bool SP2 = false>
; __device__ __forceinline__ void gemm_phase(PG8_LAS unsigned char* lds, const Gemm g, const Sched& S, const Epi& E) {
;     ...
;         if constexpr (ALIGN_EPI) { if (wr == 0) PG8_BAR; }
;         if constexpr (!Epi::AFTER_DRAIN) { E(acc, cur, wr, wc, fr, fq); S.done(cur); }
.LBB0_82:
	v_readlane_b32 s22, v253, 28
	v_lshl_add_u32 v151, s12, 8, v1
	v_lshl_or_b32 v152, s41, 8, v147
	v_readlane_b32 s23, v253, 29
	v_add_u32_e32 v158, 0x80, v151
	v_ashrrev_i32_e32 v153, 31, v152
	v_mov_b64_e32 v[154:155], s[22:23]
	v_mad_i64_i32 v[156:157], s[22:23], v151, s40, v[154:155]
	v_lshlrev_b64 v[152:153], 1, v[152:153]
	v_cvt_pk_bf16_f32 v110, v110, v111
	v_cvt_pk_bf16_f32 v111, v112, v113
	v_cvt_pk_bf16_f32 v112, v106, v107
	v_or_b32_e32 v106, 16, v151
	v_cvt_pk_bf16_f32 v70, v70, v71
	v_cvt_pk_bf16_f32 v71, v72, v73
	v_cvt_pk_bf16_f32 v72, v66, v67
	v_mad_i64_i32 v[66:67], s[22:23], v158, s40, v[154:155]
	v_cvt_pk_bf16_f32 v46, v46, v47
	v_cvt_pk_bf16_f32 v47, v48, v49
	v_cvt_pk_bf16_f32 v48, v42, v43
	v_add_u32_e32 v42, 0x90, v151
	v_lshl_add_u64 v[156:157], v[156:157], 0, v[152:153]
	v_cvt_pk_bf16_f32 v113, v108, v109
	v_mad_i64_i32 v[106:107], s[22:23], v106, s40, v[154:155]
	v_cvt_pk_bf16_f32 v94, v94, v95
	v_cvt_pk_bf16_f32 v95, v96, v97
	v_cvt_pk_bf16_f32 v96, v90, v91
	v_or_b32_e32 v90, 32, v151
	v_lshl_add_u64 v[66:67], v[66:67], 0, v[152:153]
	v_cvt_pk_bf16_f32 v49, v44, v45
	v_mad_i64_i32 v[42:43], s[22:23], v42, s40, v[154:155]
	v_cvt_pk_bf16_f32 v30, v30, v31
	v_cvt_pk_bf16_f32 v31, v32, v33
	v_cvt_pk_bf16_f32 v32, v26, v27
	v_add_u32_e32 v26, 0xa0, v151
	v_add_u32_e32 v159, 0xb0, v151
	global_store_dwordx4 v[156:157], v[110:113], off offset:256
	v_cvt_pk_bf16_f32 v97, v92, v93
	v_mad_i64_i32 v[90:91], s[22:23], v90, s40, v[154:155]
	v_lshl_add_u64 v[110:111], v[106:107], 0, v[152:153]
	v_cvt_pk_bf16_f32 v78, v78, v79
	v_cvt_pk_bf16_f32 v79, v80, v81
	v_cvt_pk_bf16_f32 v80, v74, v75
	v_or_b32_e32 v74, 48, v151
	global_store_dwordx4 v[66:67], v[46:49], off offset:256
	v_cvt_pk_bf16_f32 v33, v28, v29
	v_mad_i64_i32 v[26:27], s[22:23], v26, s40, v[154:155]
	v_lshl_add_u64 v[46:47], v[42:43], 0, v[152:153]
	global_store_dwordx4 v[110:111], v[94:97], off offset:256
	v_cvt_pk_bf16_f32 v81, v76, v77
	v_mad_i64_i32 v[74:75], s[22:23], v74, s40, v[154:155]
	v_lshl_add_u64 v[94:95], v[90:91], 0, v[152:153]
	global_store_dwordx4 v[46:47], v[30:33], off offset:256
	v_cvt_pk_bf16_f32 v14, v14, v15
	v_cvt_pk_bf16_f32 v15, v16, v17
	v_lshl_add_u64 v[30:31], v[26:27], 0, v[152:153]
	v_cvt_pk_bf16_f32 v16, v10, v11
	v_cvt_pk_bf16_f32 v17, v12, v13
	v_mad_i64_i32 v[10:11], s[22:23], v159, s40, v[154:155]
	v_cvt_pk_bf16_f32 v126, v126, v127
	v_cvt_pk_bf16_f32 v127, v128, v129
	v_cvt_pk_bf16_f32 v128, v122, v123
	v_cvt_pk_bf16_f32 v129, v124, v125
	v_cvt_pk_bf16_f32 v106, v118, v119
	v_cvt_pk_bf16_f32 v107, v120, v121
	v_cvt_pk_bf16_f32 v108, v114, v115
	v_cvt_pk_bf16_f32 v109, v116, v117
	v_cvt_pk_bf16_f32 v90, v102, v103
	v_cvt_pk_bf16_f32 v91, v104, v105
	v_cvt_pk_bf16_f32 v92, v98, v99
	v_cvt_pk_bf16_f32 v93, v100, v101
	global_store_dwordx4 v[94:95], v[78:81], off offset:256
	v_cvt_pk_bf16_f32 v76, v82, v83
	v_cvt_pk_bf16_f32 v77, v84, v85
	v_lshl_add_u64 v[78:79], v[74:75], 0, v[152:153]
	v_cvt_pk_bf16_f32 v74, v86, v87
	v_cvt_pk_bf16_f32 v75, v88, v89
	v_cvt_pk_bf16_f32 v73, v68, v69
	v_cvt_pk_bf16_f32 v62, v62, v63
	v_cvt_pk_bf16_f32 v63, v64, v65
	v_cvt_pk_bf16_f32 v64, v58, v59
	v_cvt_pk_bf16_f32 v65, v60, v61
	v_cvt_pk_bf16_f32 v42, v54, v55
	v_cvt_pk_bf16_f32 v43, v56, v57
	v_cvt_pk_bf16_f32 v44, v50, v51
	v_cvt_pk_bf16_f32 v45, v52, v53
	v_cvt_pk_bf16_f32 v26, v38, v39
	v_cvt_pk_bf16_f32 v27, v40, v41
	v_cvt_pk_bf16_f32 v28, v34, v35
	v_cvt_pk_bf16_f32 v29, v36, v37
	global_store_dwordx4 v[30:31], v[14:17], off offset:256
	v_cvt_pk_bf16_f32 v12, v18, v19
	v_cvt_pk_bf16_f32 v13, v20, v21
	v_lshl_add_u64 v[14:15], v[10:11], 0, v[152:153]
	v_cvt_pk_bf16_f32 v10, v22, v23
	v_cvt_pk_bf16_f32 v11, v24, v25
	v_cvt_pk_bf16_f32 v6, v6, v7
	v_cvt_pk_bf16_f32 v7, v8, v9
	v_cvt_pk_bf16_f32 v8, v2, v3
	v_cvt_pk_bf16_f32 v9, v4, v5
	s_andn2_b64 vcc, exec, s[4:5]
	s_mov_b64 s[4:5], -1
	global_store_dwordx4 v[156:157], v[126:129], off
	global_store_dwordx4 v[110:111], v[106:109], off
	global_store_dwordx4 v[94:95], v[90:93], off
	global_store_dwordx4 v[78:79], v[74:77], off
	global_store_dwordx4 v[78:79], v[70:73], off offset:256
	global_store_dwordx4 v[66:67], v[62:65], off
	global_store_dwordx4 v[46:47], v[42:45], off
	global_store_dwordx4 v[30:31], v[26:29], off
	global_store_dwordx4 v[14:15], v[10:13], off
	global_store_dwordx4 v[14:15], v[6:9], off offset:256
	s_cmp_eq_u64 s[10:11], 0
	s_cbranch_scc1 .Lg1_noalign
	s_barrier
.Lg1_noalign:
	s_cbranch_vccnz .LBB0_75
	s_andn2_b64 vcc, exec, s[6:7]
	s_cbranch_vccnz .LBB0_74
	s_barrier
	s_branch .LBB0_74

; DI unsigned cvt_pk_bf16(float lo, float hi) { f32x2 v = {lo, hi}; bf16v2 b = __builtin_convertvector(v, bf16v2); return __builtin_bit_cast(unsigned, b); }
;     DI void operator()(const f32x4 (&acc)[2][2][4][2], const Unit& u, int wr, int wc, int fr, int fq) const {
;         const int row0 = u.pm * BM + wr * 64 + fr; const int col0 = u.pn * BM + wc * 32 + 8 * fq;
;         float rs[2][4];
; #pragma unroll
;         for (int ai = 0; ai < 2; ++ai)
; #pragma unroll
;             for (int m = 0; m < 4; ++m) rs[ai][m] = ssq ? __builtin_amdgcn_rsqf(ssq[row0 + ai * HALF + m * 16] * (1.0f / 4096.0f) + 1e-6f) : 1.0f;
; #pragma unroll
;         for (int ai = 0; ai < 2; ++ai)
; #pragma unroll
;             for (int m = 0; m < 4; ++m) { bf16_t* rowp = O + (size_t)(row0 + ai * HALF + m * 16) * ldc + col0; const float s = rs[ai][m];
; #pragma unroll
;                 for (int bj = 0; bj < 2; ++bj) { const f32x4 v0 = acc[ai][bj][m][0] * s, v1 = acc[ai][bj][m][1] * s;
;                     u32x4 w; w.x = cvt_pk_bf16(v0[0], v0[1]); w.y = cvt_pk_bf16(v0[2], v0[3]); w.z = cvt_pk_bf16(v1[0], v1[1]); w.w = cvt_pk_bf16(v1[2], v1[3]);
;                     *(u32x4*)(rowp + bj * HALF) = w; } }
.LBB0_528:
	v_lshl_add_u32 v148, s20, 8, v157
	v_ashrrev_i32_e32 v149, 31, v148
	v_lshl_add_u64 v[146:147], v[148:149], 2, s[8:9]
	global_load_dword v149, v[146:147], off
	global_load_dword v150, v[146:147], off offset:64
	global_load_dword v167, v[146:147], off offset:128
	global_load_dword v174, v[146:147], off offset:192
	global_load_dword v175, v[146:147], off offset:512
	global_load_dword v176, v[146:147], off offset:576
	global_load_dword v177, v[146:147], off offset:640
	global_load_dword v178, v[146:147], off offset:704
	v_readlane_b32 s22, v253, 28
	v_lshl_or_b32 v164, s41, 8, v159
	v_readlane_b32 s23, v253, 29
	v_ashrrev_i32_e32 v165, 31, v164
	v_add_u32_e32 v179, 0x80, v148
	v_mov_b64_e32 v[146:147], s[22:23]
	v_mad_i64_i32 v[168:169], s[22:23], v148, s40, v[146:147]
	v_or_b32_e32 v170, 16, v148
	v_or_b32_e32 v172, 32, v148
	v_lshlrev_b64 v[164:165], 1, v[164:165]
	v_mad_i64_i32 v[170:171], s[22:23], v170, s40, v[146:147]
	v_mad_i64_i32 v[172:173], s[22:23], v172, s40, v[146:147]
	v_lshl_add_u64 v[168:169], v[168:169], 0, v[164:165]
	v_lshl_add_u64 v[170:171], v[170:171], 0, v[164:165]
	v_lshl_add_u64 v[172:173], v[172:173], 0, v[164:165]
	v_add_u32_e32 v181, 0xb0, v148
	s_andn2_b64 vcc, exec, s[0:1]
	s_mov_b64 s[0:1], -1
	s_waitcnt vmcnt(0)
	v_fmamk_f32 v149, v149, 0x39800000, v163
	v_fmamk_f32 v150, v150, 0x39800000, v163
	v_fmamk_f32 v167, v167, 0x39800000, v163
	v_fmamk_f32 v180, v174, 0x39800000, v163
	v_rsq_f32_e32 v174, v149
	v_fmamk_f32 v183, v176, 0x39800000, v163
	v_rsq_f32_e32 v176, v150
	v_fmamk_f32 v185, v178, 0x39800000, v163
	v_rsq_f32_e32 v178, v167
	v_fmamk_f32 v175, v175, 0x39800000, v163
	v_fmamk_f32 v177, v177, 0x39800000, v163
	v_pk_mul_f32 v[128:129], v[128:129], v[174:175] op_sel_hi:[1,0]
	v_pk_mul_f32 v[126:127], v[126:127], v[174:175] op_sel_hi:[1,0]
	v_pk_mul_f32 v[124:125], v[124:125], v[174:175] op_sel_hi:[1,0]
	v_pk_mul_f32 v[122:123], v[122:123], v[174:175] op_sel_hi:[1,0]
	v_rsq_f32_e32 v182, v175
	v_rsq_f32_e32 v186, v177
	v_pk_mul_f32 v[108:109], v[108:109], v[174:175] op_sel_hi:[1,0]
	v_pk_mul_f32 v[106:107], v[106:107], v[174:175] op_sel_hi:[1,0]
	v_pk_mul_f32 v[104:105], v[104:105], v[174:175] op_sel_hi:[1,0]
	v_pk_mul_f32 v[102:103], v[102:103], v[174:175] op_sel_hi:[1,0]
	v_pk_mul_f32 v[120:121], v[120:121], v[176:177] op_sel_hi:[1,0]
	v_pk_mul_f32 v[118:119], v[118:119], v[176:177] op_sel_hi:[1,0]
	v_pk_mul_f32 v[116:117], v[116:117], v[176:177] op_sel_hi:[1,0]
	v_pk_mul_f32 v[114:115], v[114:115], v[176:177] op_sel_hi:[1,0]
	v_pk_mul_f32 v[174:175], v[96:97], v[176:177] op_sel_hi:[1,0]
	v_pk_mul_f32 v[188:189], v[94:95], v[176:177] op_sel_hi:[1,0]
	v_pk_mul_f32 v[190:191], v[92:93], v[176:177] op_sel_hi:[1,0]
	v_pk_mul_f32 v[176:177], v[90:91], v[176:177] op_sel_hi:[1,0]
	v_pk_mul_f32 v[112:113], v[112:113], v[178:179] op_sel_hi:[1,0]
	v_pk_mul_f32 v[110:111], v[110:111], v[178:179] op_sel_hi:[1,0]
	v_pk_mul_f32 v[192:193], v[100:101], v[178:179] op_sel_hi:[1,0]
	v_pk_mul_f32 v[194:195], v[98:99], v[178:179] op_sel_hi:[1,0]
	v_pk_mul_f32 v[196:197], v[88:89], v[178:179] op_sel_hi:[1,0]
	v_pk_mul_f32 v[198:199], v[86:87], v[178:179] op_sel_hi:[1,0]
	v_cvt_pk_bf16_f32 v86, v126, v127
	v_cvt_pk_bf16_f32 v87, v128, v129
	v_cvt_pk_bf16_f32 v88, v122, v123
	v_cvt_pk_bf16_f32 v89, v124, v125
	v_rsq_f32_e32 v180, v180
	v_cvt_pk_bf16_f32 v90, v106, v107
	v_cvt_pk_bf16_f32 v91, v108, v109
	v_cvt_pk_bf16_f32 v92, v102, v103
	v_cvt_pk_bf16_f32 v93, v104, v105
	v_cvt_pk_bf16_f32 v94, v118, v119
	v_cvt_pk_bf16_f32 v95, v120, v121
	v_cvt_pk_bf16_f32 v96, v114, v115
	v_cvt_pk_bf16_f32 v97, v116, v117
	v_cvt_pk_bf16_f32 v98, v188, v189
	v_cvt_pk_bf16_f32 v99, v174, v175
	v_cvt_pk_bf16_f32 v100, v176, v177
	v_cvt_pk_bf16_f32 v101, v190, v191
	v_cvt_pk_bf16_f32 v102, v110, v111
	v_cvt_pk_bf16_f32 v103, v112, v113
	v_cvt_pk_bf16_f32 v104, v194, v195
	v_cvt_pk_bf16_f32 v105, v192, v193
	global_store_dwordx4 v[168:169], v[86:89], off
	global_store_dwordx4 v[168:169], v[90:93], off offset:256
	global_store_dwordx4 v[170:171], v[94:97], off
	global_store_dwordx4 v[170:171], v[98:101], off offset:256
	global_store_dwordx4 v[172:173], v[102:105], off
	v_pk_mul_f32 v[86:87], v[76:77], v[178:179] op_sel_hi:[1,0]
	v_pk_mul_f32 v[76:77], v[74:75], v[178:179] op_sel_hi:[1,0]
	v_cvt_pk_bf16_f32 v74, v198, v199
	v_cvt_pk_bf16_f32 v75, v196, v197
	v_cvt_pk_bf16_f32 v76, v76, v77
	v_cvt_pk_bf16_f32 v77, v86, v87
	global_store_dwordx4 v[172:173], v[74:77], off offset:256
	v_pk_mul_f32 v[80:81], v[80:81], v[180:181] op_sel_hi:[1,0]
	v_pk_mul_f32 v[78:79], v[78:79], v[180:181] op_sel_hi:[1,0]
	v_or_b32_e32 v74, 48, v148
	v_mad_i64_i32 v[74:75], s[22:23], v74, s40, v[146:147]
	v_lshl_add_u64 v[86:87], v[74:75], 0, v[164:165]
	v_pk_mul_f32 v[76:77], v[84:85], v[180:181] op_sel_hi:[1,0]
; DI unsigned cvt_pk_bf16(float lo, float hi) { f32x2 v = {lo, hi}; bf16v2 b = __builtin_convertvector(v, bf16v2); return __builtin_bit_cast(unsigned, b); }
; #define PG8_BAR __builtin_amdgcn_s_barrier()
;     DI void operator()(const f32x4 (&acc)[2][2][4][2], const Unit& u, int wr, int wc, int fr, int fq) const {
;     ...
;             for (int m = 0; m < 4; ++m) { bf16_t* rowp = O + (size_t)(row0 + ai * HALF + m * 16) * ldc + col0; const float s = rs[ai][m];
; #pragma unroll
;                 for (int bj = 0; bj < 2; ++bj) { const f32x4 v0 = acc[ai][bj][m][0] * s, v1 = acc[ai][bj][m][1] * s;
;                     u32x4 w; w.x = cvt_pk_bf16(v0[0], v0[1]); w.y = cvt_pk_bf16(v0[2], v0[3]); w.z = cvt_pk_bf16(v1[0], v1[1]); w.w = cvt_pk_bf16(v1[2], v1[3]);
;                     *(u32x4*)(rowp + bj * HALF) = w; } }
; template <class Epi, class Sched, bool ALIGN_EPI = false, bool SP2 = false>
; __device__ __forceinline__ void gemm_phase(PG8_LAS unsigned char* lds, const Gemm g, const Sched& S, const Epi& E) {
;     ...
;         if constexpr (ALIGN_EPI) { if (wr == 0) PG8_BAR; }
;         if constexpr (!Epi::AFTER_DRAIN) { E(acc, cur, wr, wc, fr, fq); S.done(cur); }
;         if (!has_next) break;
	v_pk_mul_f32 v[74:75], v[82:83], v[180:181] op_sel_hi:[1,0]
	v_pk_mul_f32 v[72:73], v[72:73], v[180:181] op_sel_hi:[1,0]
	v_cvt_pk_bf16_f32 v74, v74, v75
	v_cvt_pk_bf16_f32 v75, v76, v77
	v_cvt_pk_bf16_f32 v76, v78, v79
	v_cvt_pk_bf16_f32 v77, v80, v81
	global_store_dwordx4 v[86:87], v[74:77], off
	v_pk_mul_f32 v[70:71], v[70:71], v[180:181] op_sel_hi:[1,0]
	v_pk_mul_f32 v[64:65], v[64:65], v[182:183] op_sel_hi:[1,0]
	v_pk_mul_f32 v[74:75], v[68:69], v[180:181] op_sel_hi:[1,0]
	v_pk_mul_f32 v[68:69], v[66:67], v[180:181] op_sel_hi:[1,0]
	v_cvt_pk_bf16_f32 v66, v70, v71
	v_cvt_pk_bf16_f32 v67, v72, v73
	v_cvt_pk_bf16_f32 v68, v68, v69
	v_cvt_pk_bf16_f32 v69, v74, v75
	global_store_dwordx4 v[86:87], v[66:69], off offset:256
	v_pk_mul_f32 v[62:63], v[62:63], v[182:183] op_sel_hi:[1,0]
	v_rsq_f32_e32 v184, v183
	v_mad_i64_i32 v[66:67], s[22:23], v179, s40, v[146:147]
	v_pk_mul_f32 v[68:69], v[60:61], v[182:183] op_sel_hi:[1,0]
	v_pk_mul_f32 v[60:61], v[58:59], v[182:183] op_sel_hi:[1,0]
	v_lshl_add_u64 v[66:67], v[66:67], 0, v[164:165]
	v_cvt_pk_bf16_f32 v58, v62, v63
	v_cvt_pk_bf16_f32 v59, v64, v65
	v_cvt_pk_bf16_f32 v60, v60, v61
	v_cvt_pk_bf16_f32 v61, v68, v69
	global_store_dwordx4 v[66:67], v[58:61], off
	v_pk_mul_f32 v[52:53], v[52:53], v[182:183] op_sel_hi:[1,0]
	v_pk_mul_f32 v[50:51], v[50:51], v[182:183] op_sel_hi:[1,0]
	v_pk_mul_f32 v[58:59], v[44:45], v[182:183] op_sel_hi:[1,0]
	v_pk_mul_f32 v[44:45], v[42:43], v[182:183] op_sel_hi:[1,0]
	v_cvt_pk_bf16_f32 v42, v50, v51
	v_cvt_pk_bf16_f32 v43, v52, v53
	v_cvt_pk_bf16_f32 v44, v44, v45
	v_cvt_pk_bf16_f32 v45, v58, v59
	global_store_dwordx4 v[66:67], v[42:45], off offset:256
	v_pk_mul_f32 v[48:49], v[48:49], v[184:185] op_sel_hi:[1,0]
	v_pk_mul_f32 v[46:47], v[46:47], v[184:185] op_sel_hi:[1,0]
	v_add_u32_e32 v42, 0x90, v148
	v_mad_i64_i32 v[42:43], s[22:23], v42, s40, v[146:147]
	v_lshl_add_u64 v[50:51], v[42:43], 0, v[164:165]
	v_pk_mul_f32 v[44:45], v[56:57], v[184:185] op_sel_hi:[1,0]
	v_pk_mul_f32 v[42:43], v[54:55], v[184:185] op_sel_hi:[1,0]
	v_pk_mul_f32 v[36:37], v[36:37], v[184:185] op_sel_hi:[1,0]
	v_cvt_pk_bf16_f32 v42, v42, v43
	v_cvt_pk_bf16_f32 v43, v44, v45
	v_cvt_pk_bf16_f32 v44, v46, v47
	v_cvt_pk_bf16_f32 v45, v48, v49
	global_store_dwordx4 v[50:51], v[42:45], off
	v_pk_mul_f32 v[34:35], v[34:35], v[184:185] op_sel_hi:[1,0]
	v_pk_mul_f32 v[32:33], v[32:33], v[186:187] op_sel_hi:[1,0]
	v_pk_mul_f32 v[42:43], v[28:29], v[184:185] op_sel_hi:[1,0]
	v_pk_mul_f32 v[28:29], v[26:27], v[184:185] op_sel_hi:[1,0]
	v_cvt_pk_bf16_f32 v26, v34, v35
	v_cvt_pk_bf16_f32 v27, v36, v37
	v_cvt_pk_bf16_f32 v28, v28, v29
	v_cvt_pk_bf16_f32 v29, v42, v43
	global_store_dwordx4 v[50:51], v[26:29], off offset:256
	v_pk_mul_f32 v[30:31], v[30:31], v[186:187] op_sel_hi:[1,0]
	v_rsq_f32_e32 v150, v185
	v_add_u32_e32 v26, 0xa0, v148
	v_mad_i64_i32 v[26:27], s[22:23], v26, s40, v[146:147]
	v_lshl_add_u64 v[34:35], v[26:27], 0, v[164:165]
	v_pk_mul_f32 v[28:29], v[40:41], v[186:187] op_sel_hi:[1,0]
	v_pk_mul_f32 v[26:27], v[38:39], v[186:187] op_sel_hi:[1,0]
	v_pk_mul_f32 v[20:21], v[20:21], v[186:187] op_sel_hi:[1,0]
	v_cvt_pk_bf16_f32 v26, v26, v27
	v_cvt_pk_bf16_f32 v27, v28, v29
	v_cvt_pk_bf16_f32 v28, v30, v31
	v_cvt_pk_bf16_f32 v29, v32, v33
	global_store_dwordx4 v[34:35], v[26:29], off
	v_pk_mul_f32 v[18:19], v[18:19], v[186:187] op_sel_hi:[1,0]
	v_pk_mul_f32 v[16:17], v[16:17], v[150:151] op_sel_hi:[1,0]
	v_pk_mul_f32 v[26:27], v[12:13], v[186:187] op_sel_hi:[1,0]
	v_pk_mul_f32 v[12:13], v[10:11], v[186:187] op_sel_hi:[1,0]
	v_cvt_pk_bf16_f32 v10, v18, v19
	v_cvt_pk_bf16_f32 v11, v20, v21
	v_cvt_pk_bf16_f32 v12, v12, v13
	v_cvt_pk_bf16_f32 v13, v26, v27
	global_store_dwordx4 v[34:35], v[10:13], off offset:256
	v_pk_mul_f32 v[14:15], v[14:15], v[150:151] op_sel_hi:[1,0]
	v_pk_mul_f32 v[8:9], v[8:9], v[150:151] op_sel_hi:[1,0]
	v_mad_i64_i32 v[10:11], s[22:23], v181, s40, v[146:147]
	v_lshl_add_u64 v[18:19], v[10:11], 0, v[164:165]
	v_pk_mul_f32 v[12:13], v[24:25], v[150:151] op_sel_hi:[1,0]
	v_pk_mul_f32 v[10:11], v[22:23], v[150:151] op_sel_hi:[1,0]
	v_pk_mul_f32 v[6:7], v[6:7], v[150:151] op_sel_hi:[1,0]
	v_cvt_pk_bf16_f32 v10, v10, v11
	v_cvt_pk_bf16_f32 v11, v12, v13
	v_cvt_pk_bf16_f32 v12, v14, v15
	v_cvt_pk_bf16_f32 v13, v16, v17
	global_store_dwordx4 v[18:19], v[10:13], off
	s_nop 1
	v_pk_mul_f32 v[10:11], v[4:5], v[150:151] op_sel_hi:[1,0]
	v_pk_mul_f32 v[4:5], v[2:3], v[150:151] op_sel_hi:[1,0]
	v_cvt_pk_bf16_f32 v2, v6, v7
	v_cvt_pk_bf16_f32 v3, v8, v9
	v_cvt_pk_bf16_f32 v4, v4, v5
	v_cvt_pk_bf16_f32 v5, v10, v11
	global_store_dwordx4 v[18:19], v[2:5], off offset:256
	s_cmp_eq_u64 s[10:11], 0
	s_cbranch_scc1 .Lg3_noalign
	s_barrier
.Lg3_noalign:
	s_cbranch_vccnz .LBB0_521
	s_andn2_b64 vcc, exec, s[4:5]
	s_cbranch_vccnz .LBB0_520
	s_barrier
	s_branch .LBB0_520
